# P2 K-loop restructured like P7 (64 MFMA per barrier pair, split staging)
# speedup vs baseline: 1.0087x; 1.0026x over previous
.LBB0_210:
	s_and_b32 s3, s3, 3
	s_lshl_b32 s12, s2, 13
	s_lshl_b32 s13, s3, 9
	s_add_u32 s4, s88, 0x188800
	s_addc_u32 s5, s89, 0
	s_add_i32 m0, s68, 0x18000
	v_lshl_add_u64 v[8:9], s[4:5], 0, v[132:133]
	s_waitcnt vmcnt(0)
	s_barrier
	global_load_lds_dwordx4 v[8:9], off
	v_lshl_add_u64 v[8:9], s[4:5], 0, v[136:137]
	s_add_i32 m0, s68, 0x1a000
	s_mov_b64 s[52:53], 0x80
	s_add_i32 s8, s68, 0x8000
	s_add_i32 s9, s68, 0xa000
	global_load_lds_dwordx4 v[8:9], off
	v_lshl_add_u64 v[2:3], v[2:3], 0, s[52:53]
	s_mov_b32 m0, s8
	s_add_u32 s4, s88, 0x189000
	global_load_lds_dwordx4 v[2:3], off
	v_lshl_add_u64 v[2:3], v[4:5], 0, s[52:53]
	s_mov_b32 m0, s9
	s_addc_u32 s5, s89, 0
	global_load_lds_dwordx4 v[2:3], off
	s_add_i32 m0, s68, 0x1c000
	v_lshl_add_u64 v[2:3], s[4:5], 0, v[132:133]
	global_load_lds_dwordx4 v[2:3], off
	v_lshl_add_u64 v[2:3], s[4:5], 0, v[136:137]
	s_add_i32 m0, s68, 0x1e000
	v_and_b32_e32 v1, 15, v6
	global_load_lds_dwordx4 v[2:3], off
	v_bfe_u32 v2, v6, 4, 2
	v_lshlrev_b32_e32 v3, 4, v2
	v_lshlrev_b32_e32 v4, 2, v6
	v_lshl_or_b32 v3, v1, 6, v3
	v_and_b32_e32 v4, 32, v4
	v_lshlrev_b32_e32 v2, 11, v2
	v_lshlrev_b32_e32 v1, 4, v1
	s_cmpk_lt_u32 s0, 0x100
	v_bitop3_b32 v3, v3, s12, v4 bitop3:0xde
	v_or3_b32 v1, s13, v1, v2
	s_cselect_b64 s[66:67], -1, 0
	v_bfe_u32 v2, v6, 2, 4
	v_and_b32_e32 v4, 3, v6
	s_ashr_i32 s0, s92, 31
	v_lshl_or_b32 v143, s2, 6, v2
	v_lshlrev_b32_e32 v2, 3, v4
	v_writelane_b32 v249, s0, 58
	v_lshl_or_b32 v144, s3, 5, v2
	v_readlane_b32 s2, v249, 2
	s_mov_b32 s0, s2
	s_ashr_i32 s2, s2, 31
	v_readlane_b32 s3, v249, 3
	v_writelane_b32 v249, s2, 60
	s_and_b32 s2, s0, 7
	s_waitcnt vmcnt(6)
	v_writelane_b32 v249, s2, 61
	s_bfe_u32 s2, s0, 0x30003
	v_and_b32_e32 v5, 60, v6
	v_writelane_b32 v249, s2, 62
	s_ashr_i32 s0, s0, 6
	v_lshl_or_b32 v142, v4, 6, v5
	v_writelane_b32 v249, s0, 63
	v_mov_b32_e32 v146, s1
	s_add_i32 s0, 0, 0x10000
	s_add_i32 s1, 0, 0x14000
	v_add_u32_e32 v145, 0, v3
	s_movk_i32 s72, 0x6080
	v_mov_b64_e32 v[138:139], 0x8ff
	s_barrier
	s_branch .LBB0_213

.LBB0_249:
	s_lshl_b32 s2, s87, 7
	s_add_u32 s12, s84, s2
	s_addc_u32 s13, s85, 0
	s_add_u32 s98, s12, 0x80
	s_addc_u32 s99, s13, 0
	s_add_u32 s4, s12, 0x100
	s_addc_u32 s5, s13, 0
	s_and_b64 s[2:3], s[92:93], exec
	s_cselect_b32 s5, s5, s81
	s_cselect_b32 s4, s4, s80
	s_mul_i32 s2, s87, 0x188800
	s_add_u32 s2, s88, s2
	s_addc_u32 s3, s89, 0
	s_add_u32 s100, s2, 0x188800
	s_addc_u32 s101, s3, 0
	s_add_u32 s20, s2, 0x311000
	s_addc_u32 s21, s3, 0
	s_and_b64 s[2:3], s[92:93], exec
	s_cselect_b32 s92, s20, s86
	s_cselect_b32 s93, s21, s75
	s_cmp_lt_u32 s68, 0x1000
	s_cbranch_scc0 .Lg2p2_0_hi
	s_add_u32 s2, s100, 0x0
	s_addc_u32 s3, s101, 0
	v_lshl_add_u64 v[140:141], s[2:3], 0, v[132:133]
	s_add_i32 m0, s68, 0x18000
	s_add_u32 s2, s2, 0x62200
	s_addc_u32 s3, s3, 0
	global_load_lds_dwordx4 v[140:141], off
	v_lshl_add_u64 v[212:213], s[2:3], 0, v[132:133]
	s_add_i32 m0, s68, 0x19000
	s_add_u32 s2, s2, 0x62200
	s_addc_u32 s3, s3, 0
	global_load_lds_dwordx4 v[212:213], off
	v_lshl_add_u64 v[140:141], s[2:3], 0, v[132:133]
	s_add_i32 m0, s68, 0x1a000
	s_add_u32 s2, s2, 0x62200
	s_addc_u32 s3, s3, 0
	global_load_lds_dwordx4 v[140:141], off
	v_lshl_add_u64 v[212:213], s[2:3], 0, v[132:133]
	s_add_i32 m0, s68, 0x1b000
	s_nop 0
	global_load_lds_dwordx4 v[212:213], off
	s_add_u32 s2, s98, 0x0
	s_addc_u32 s3, s99, 0
	v_lshl_add_u64 v[140:141], s[2:3], 0, v[130:131]
	s_add_i32 m0, s68, 0x8000
	s_add_u32 s2, s2, 0x41000
	s_addc_u32 s3, s3, 0
	global_load_lds_dwordx4 v[140:141], off
	v_lshl_add_u64 v[212:213], s[2:3], 0, v[130:131]
	s_add_i32 m0, s68, 0x9000
	s_add_u32 s2, s2, 0x41000
	s_addc_u32 s3, s3, 0
	global_load_lds_dwordx4 v[212:213], off
	v_lshl_add_u64 v[140:141], s[2:3], 0, v[130:131]
	s_add_i32 m0, s68, 0xa000
	s_add_u32 s2, s2, 0x41000
	s_addc_u32 s3, s3, 0
	global_load_lds_dwordx4 v[140:141], off
	v_lshl_add_u64 v[212:213], s[2:3], 0, v[130:131]
	s_add_i32 m0, s68, 0xb000
	s_nop 0
	global_load_lds_dwordx4 v[212:213], off
	s_branch .Lg2p2_0_done
.Lg2p2_0_hi:
	s_sub_u32 s2, s100, 0x61a00
	s_subb_u32 s3, s101, 0
	v_lshl_add_u64 v[140:141], s[2:3], 0, v[132:133]
	s_add_i32 m0, s68, 0x1b000
	s_add_u32 s2, s2, 0x62200
	s_addc_u32 s3, s3, 0
	global_load_lds_dwordx4 v[140:141], off
	v_lshl_add_u64 v[212:213], s[2:3], 0, v[132:133]
	s_add_i32 m0, s68, 0x1c000
	s_add_u32 s2, s2, 0x62200
	s_addc_u32 s3, s3, 0
	global_load_lds_dwordx4 v[212:213], off
	v_lshl_add_u64 v[140:141], s[2:3], 0, v[132:133]
	s_add_i32 m0, s68, 0x1d000
	s_add_u32 s2, s2, 0x62200
	s_addc_u32 s3, s3, 0
	global_load_lds_dwordx4 v[140:141], off
	v_lshl_add_u64 v[212:213], s[2:3], 0, v[132:133]
	s_add_i32 m0, s68, 0x1e000
	s_nop 0
	global_load_lds_dwordx4 v[212:213], off
	s_add_u32 s2, s98, 0xc3000
	s_addc_u32 s3, s99, 0
	v_lshl_add_u64 v[140:141], s[2:3], 0, v[130:131]
	s_add_i32 m0, s68, 0xb000
	s_add_u32 s2, s2, 0x41000
	s_addc_u32 s3, s3, 0
	global_load_lds_dwordx4 v[140:141], off
	v_lshl_add_u64 v[212:213], s[2:3], 0, v[130:131]
	s_add_i32 m0, s68, 0xc000
	s_add_u32 s2, s2, 0x41000
	s_addc_u32 s3, s3, 0
	global_load_lds_dwordx4 v[212:213], off
	v_lshl_add_u64 v[140:141], s[2:3], 0, v[130:131]
	s_add_i32 m0, s68, 0xd000
	s_add_u32 s2, s2, 0x41000
	s_addc_u32 s3, s3, 0
	global_load_lds_dwordx4 v[140:141], off
	v_lshl_add_u64 v[212:213], s[2:3], 0, v[130:131]
	s_add_i32 m0, s68, 0xe000
	s_nop 0
	global_load_lds_dwordx4 v[212:213], off
.Lg2p2_0_done:
	s_add_i32 s2, 0, 0x10000
	v_add_u32_e32 v147, s2, v1
	ds_read_b128 v[148:151], v147
	ds_read_b128 v[152:155], v147 offset:256
	ds_read_b128 v[156:159], v147 offset:8192
	ds_read_b128 v[160:163], v147 offset:8448
	ds_read_b128 v[180:183], v145
	ds_read_b128 v[184:187], v145 offset:1024
	ds_read_b128 v[188:191], v145 offset:2048
	ds_read_b128 v[192:195], v145 offset:3072
	ds_read_b128 v[196:199], v145 offset:4096
	ds_read_b128 v[200:203], v145 offset:5120
	ds_read_b128 v[204:207], v145 offset:6144
	ds_read_b128 v[208:211], v145 offset:7168
	s_waitcnt lgkmcnt(0)
	s_barrier
	s_setprio 1
	s_add_i32 s2, 0, 0x14000
	v_add_u32_e32 v147, s2, v1
	v_mfma_f32_16x16x32_bf16 v[126:129], v[148:151], v[180:183], v[126:129]
	v_mfma_f32_16x16x32_bf16 v[122:125], v[152:155], v[180:183], v[122:125]
	ds_read_b128 v[164:167], v147
	v_mfma_f32_16x16x32_bf16 v[118:121], v[148:151], v[188:191], v[118:121]
	v_mfma_f32_16x16x32_bf16 v[110:113], v[152:155], v[188:191], v[110:113]
	ds_read_b128 v[168:171], v147 offset:256
	v_mfma_f32_16x16x32_bf16 v[102:105], v[148:151], v[196:199], v[102:105]
	v_mfma_f32_16x16x32_bf16 v[94:97], v[152:155], v[196:199], v[94:97]
	ds_read_b128 v[172:175], v147 offset:8192
	v_mfma_f32_16x16x32_bf16 v[86:89], v[148:151], v[204:207], v[86:89]
	v_mfma_f32_16x16x32_bf16 v[78:81], v[152:155], v[204:207], v[78:81]
	ds_read_b128 v[176:179], v147 offset:8448
	v_mfma_f32_16x16x32_bf16 v[126:129], v[156:159], v[184:187], v[126:129]
	v_mfma_f32_16x16x32_bf16 v[122:125], v[160:163], v[184:187], v[122:125]
	ds_read_b128 v[216:219], v145 offset:16384
	v_mfma_f32_16x16x32_bf16 v[118:121], v[156:159], v[192:195], v[118:121]
	v_mfma_f32_16x16x32_bf16 v[110:113], v[160:163], v[192:195], v[110:113]
	ds_read_b128 v[220:223], v145 offset:17408
	v_mfma_f32_16x16x32_bf16 v[102:105], v[156:159], v[200:203], v[102:105]
	v_mfma_f32_16x16x32_bf16 v[94:97], v[160:163], v[200:203], v[94:97]
	ds_read_b128 v[224:227], v145 offset:18432
	v_mfma_f32_16x16x32_bf16 v[86:89], v[156:159], v[208:211], v[86:89]
	v_mfma_f32_16x16x32_bf16 v[78:81], v[160:163], v[208:211], v[78:81]
	ds_read_b128 v[228:231], v145 offset:19456
	s_waitcnt lgkmcnt(4)
	v_mfma_f32_16x16x32_bf16 v[114:117], v[164:167], v[180:183], v[114:117]
	v_mfma_f32_16x16x32_bf16 v[106:109], v[168:171], v[180:183], v[106:109]
	ds_read_b128 v[232:235], v145 offset:20480
	v_mfma_f32_16x16x32_bf16 v[98:101], v[164:167], v[188:191], v[98:101]
	v_mfma_f32_16x16x32_bf16 v[90:93], v[168:171], v[188:191], v[90:93]
	ds_read_b128 v[236:239], v145 offset:21504
	v_mfma_f32_16x16x32_bf16 v[82:85], v[164:167], v[196:199], v[82:85]
	v_mfma_f32_16x16x32_bf16 v[74:77], v[168:171], v[196:199], v[74:77]
	ds_read_b128 v[240:243], v145 offset:22528
	v_mfma_f32_16x16x32_bf16 v[70:73], v[164:167], v[204:207], v[70:73]
	v_mfma_f32_16x16x32_bf16 v[66:69], v[168:171], v[204:207], v[66:69]
	ds_read_b128 v[244:247], v145 offset:23552
	v_mfma_f32_16x16x32_bf16 v[114:117], v[172:175], v[184:187], v[114:117]
	v_mfma_f32_16x16x32_bf16 v[106:109], v[176:179], v[184:187], v[106:109]
	v_mfma_f32_16x16x32_bf16 v[98:101], v[172:175], v[192:195], v[98:101]
	v_mfma_f32_16x16x32_bf16 v[90:93], v[176:179], v[192:195], v[90:93]
	v_mfma_f32_16x16x32_bf16 v[82:85], v[172:175], v[200:203], v[82:85]
	v_mfma_f32_16x16x32_bf16 v[74:77], v[176:179], v[200:203], v[74:77]
	v_mfma_f32_16x16x32_bf16 v[70:73], v[172:175], v[208:211], v[70:73]
	v_mfma_f32_16x16x32_bf16 v[66:69], v[176:179], v[208:211], v[66:69]
	s_waitcnt lgkmcnt(0)
	v_mfma_f32_16x16x32_bf16 v[62:65], v[148:151], v[216:219], v[62:65]
	v_mfma_f32_16x16x32_bf16 v[58:61], v[152:155], v[216:219], v[58:61]
	v_mfma_f32_16x16x32_bf16 v[54:57], v[148:151], v[224:227], v[54:57]
	v_mfma_f32_16x16x32_bf16 v[46:49], v[152:155], v[224:227], v[46:49]
	v_mfma_f32_16x16x32_bf16 v[38:41], v[148:151], v[232:235], v[38:41]
	v_mfma_f32_16x16x32_bf16 v[30:33], v[152:155], v[232:235], v[30:33]
	v_mfma_f32_16x16x32_bf16 v[22:25], v[148:151], v[240:243], v[22:25]
	v_mfma_f32_16x16x32_bf16 v[14:17], v[152:155], v[240:243], v[14:17]
	v_mfma_f32_16x16x32_bf16 v[62:65], v[156:159], v[220:223], v[62:65]
	v_mfma_f32_16x16x32_bf16 v[58:61], v[160:163], v[220:223], v[58:61]
	v_mfma_f32_16x16x32_bf16 v[54:57], v[156:159], v[228:231], v[54:57]
	v_mfma_f32_16x16x32_bf16 v[46:49], v[160:163], v[228:231], v[46:49]
	v_mfma_f32_16x16x32_bf16 v[38:41], v[156:159], v[236:239], v[38:41]
	v_mfma_f32_16x16x32_bf16 v[30:33], v[160:163], v[236:239], v[30:33]
	v_mfma_f32_16x16x32_bf16 v[22:25], v[156:159], v[244:247], v[22:25]
	v_mfma_f32_16x16x32_bf16 v[14:17], v[160:163], v[244:247], v[14:17]
	v_mfma_f32_16x16x32_bf16 v[50:53], v[164:167], v[216:219], v[50:53]
	v_mfma_f32_16x16x32_bf16 v[42:45], v[168:171], v[216:219], v[42:45]
	v_mfma_f32_16x16x32_bf16 v[34:37], v[164:167], v[224:227], v[34:37]
	v_mfma_f32_16x16x32_bf16 v[26:29], v[168:171], v[224:227], v[26:29]
	v_mfma_f32_16x16x32_bf16 v[18:21], v[164:167], v[232:235], v[18:21]
	v_mfma_f32_16x16x32_bf16 v[10:13], v[168:171], v[232:235], v[10:13]
	v_mfma_f32_16x16x32_bf16 v[6:9], v[164:167], v[240:243], v[6:9]
	v_mfma_f32_16x16x32_bf16 v[2:5], v[168:171], v[240:243], v[2:5]
	v_mfma_f32_16x16x32_bf16 v[50:53], v[172:175], v[220:223], v[50:53]
	v_mfma_f32_16x16x32_bf16 v[42:45], v[176:179], v[220:223], v[42:45]
	v_mfma_f32_16x16x32_bf16 v[34:37], v[172:175], v[228:231], v[34:37]
	v_mfma_f32_16x16x32_bf16 v[26:29], v[176:179], v[228:231], v[26:29]
	v_mfma_f32_16x16x32_bf16 v[18:21], v[172:175], v[236:239], v[18:21]
	v_mfma_f32_16x16x32_bf16 v[10:13], v[176:179], v[236:239], v[10:13]
	v_mfma_f32_16x16x32_bf16 v[6:9], v[172:175], v[244:247], v[6:9]
	v_mfma_f32_16x16x32_bf16 v[2:5], v[176:179], v[244:247], v[2:5]
	s_setprio 0
	s_waitcnt vmcnt(0)
	s_barrier
	s_cmp_lt_u32 s68, 0x1000
	s_cbranch_scc0 .Lg2p2_1_hi
	s_add_u32 s2, s92, 0x0
	s_addc_u32 s3, s93, 0
	v_lshl_add_u64 v[140:141], s[2:3], 0, v[132:133]
	s_add_i32 m0, s68, 0x10000
	s_add_u32 s2, s2, 0x62200
	s_addc_u32 s3, s3, 0
	global_load_lds_dwordx4 v[140:141], off
	v_lshl_add_u64 v[212:213], s[2:3], 0, v[132:133]
	s_add_i32 m0, s68, 0x11000
	s_add_u32 s2, s2, 0x62200
	s_addc_u32 s3, s3, 0
	global_load_lds_dwordx4 v[212:213], off
	v_lshl_add_u64 v[140:141], s[2:3], 0, v[132:133]
	s_add_i32 m0, s68, 0x12000
	s_add_u32 s2, s2, 0x62200
	s_addc_u32 s3, s3, 0
	global_load_lds_dwordx4 v[140:141], off
	v_lshl_add_u64 v[212:213], s[2:3], 0, v[132:133]
	s_add_i32 m0, s68, 0x13000
	s_nop 0
	global_load_lds_dwordx4 v[212:213], off
	s_add_u32 s2, s4, 0x0
	s_addc_u32 s3, s5, 0
	v_lshl_add_u64 v[140:141], s[2:3], 0, v[130:131]
	s_add_i32 m0, s68, 0x0
	s_add_u32 s2, s2, 0x41000
	s_addc_u32 s3, s3, 0
	global_load_lds_dwordx4 v[140:141], off
	v_lshl_add_u64 v[212:213], s[2:3], 0, v[130:131]
	s_add_i32 m0, s68, 0x1000
	s_add_u32 s2, s2, 0x41000
	s_addc_u32 s3, s3, 0
	global_load_lds_dwordx4 v[212:213], off
	v_lshl_add_u64 v[140:141], s[2:3], 0, v[130:131]
	s_add_i32 m0, s68, 0x2000
	s_add_u32 s2, s2, 0x41000
	s_addc_u32 s3, s3, 0
	global_load_lds_dwordx4 v[140:141], off
	v_lshl_add_u64 v[212:213], s[2:3], 0, v[130:131]
	s_add_i32 m0, s68, 0x3000
	s_nop 0
	global_load_lds_dwordx4 v[212:213], off
	s_branch .Lg2p2_1_done
.Lg2p2_1_hi:
	s_sub_u32 s2, s92, 0x61a00
	s_subb_u32 s3, s93, 0
	v_lshl_add_u64 v[140:141], s[2:3], 0, v[132:133]
	s_add_i32 m0, s68, 0x13000
	s_add_u32 s2, s2, 0x62200
	s_addc_u32 s3, s3, 0
	global_load_lds_dwordx4 v[140:141], off
	v_lshl_add_u64 v[212:213], s[2:3], 0, v[132:133]
	s_add_i32 m0, s68, 0x14000
	s_add_u32 s2, s2, 0x62200
	s_addc_u32 s3, s3, 0
	global_load_lds_dwordx4 v[212:213], off
	v_lshl_add_u64 v[140:141], s[2:3], 0, v[132:133]
	s_add_i32 m0, s68, 0x15000
	s_add_u32 s2, s2, 0x62200
	s_addc_u32 s3, s3, 0
	global_load_lds_dwordx4 v[140:141], off
	v_lshl_add_u64 v[212:213], s[2:3], 0, v[132:133]
	s_add_i32 m0, s68, 0x16000
	s_nop 0
	global_load_lds_dwordx4 v[212:213], off
	s_add_u32 s2, s4, 0xc3000
	s_addc_u32 s3, s5, 0
	v_lshl_add_u64 v[140:141], s[2:3], 0, v[130:131]
	s_add_i32 m0, s68, 0x3000
	s_add_u32 s2, s2, 0x41000
	s_addc_u32 s3, s3, 0
	global_load_lds_dwordx4 v[140:141], off
	v_lshl_add_u64 v[212:213], s[2:3], 0, v[130:131]
	s_add_i32 m0, s68, 0x4000
	s_add_u32 s2, s2, 0x41000
	s_addc_u32 s3, s3, 0
	global_load_lds_dwordx4 v[212:213], off
	v_lshl_add_u64 v[140:141], s[2:3], 0, v[130:131]
	s_add_i32 m0, s68, 0x5000
	s_add_u32 s2, s2, 0x41000
	s_addc_u32 s3, s3, 0
	global_load_lds_dwordx4 v[140:141], off
	v_lshl_add_u64 v[212:213], s[2:3], 0, v[130:131]
	s_add_i32 m0, s68, 0x6000
	s_nop 0
	global_load_lds_dwordx4 v[212:213], off
.Lg2p2_1_done:
	s_add_i32 s2, 0, 0x18000
	v_add_u32_e32 v147, s2, v1
	ds_read_b128 v[148:151], v147
	ds_read_b128 v[152:155], v147 offset:256
	ds_read_b128 v[156:159], v147 offset:8192
	ds_read_b128 v[160:163], v147 offset:8448
	ds_read_b128 v[180:183], v145 offset:32768
	ds_read_b128 v[184:187], v145 offset:33792
	ds_read_b128 v[188:191], v145 offset:34816
	ds_read_b128 v[192:195], v145 offset:35840
	ds_read_b128 v[196:199], v145 offset:36864
	ds_read_b128 v[200:203], v145 offset:37888
	ds_read_b128 v[204:207], v145 offset:38912
	ds_read_b128 v[208:211], v145 offset:39936
	s_waitcnt lgkmcnt(0)
	s_barrier
	s_setprio 1
	s_add_i32 s2, 0, 0x1c000
	v_add_u32_e32 v147, s2, v1
	v_mfma_f32_16x16x32_bf16 v[126:129], v[148:151], v[180:183], v[126:129]
	v_mfma_f32_16x16x32_bf16 v[122:125], v[152:155], v[180:183], v[122:125]
	ds_read_b128 v[164:167], v147
	v_mfma_f32_16x16x32_bf16 v[118:121], v[148:151], v[188:191], v[118:121]
	v_mfma_f32_16x16x32_bf16 v[110:113], v[152:155], v[188:191], v[110:113]
	ds_read_b128 v[168:171], v147 offset:256
	v_mfma_f32_16x16x32_bf16 v[102:105], v[148:151], v[196:199], v[102:105]
	v_mfma_f32_16x16x32_bf16 v[94:97], v[152:155], v[196:199], v[94:97]
	ds_read_b128 v[172:175], v147 offset:8192
	v_mfma_f32_16x16x32_bf16 v[86:89], v[148:151], v[204:207], v[86:89]
	v_mfma_f32_16x16x32_bf16 v[78:81], v[152:155], v[204:207], v[78:81]
	ds_read_b128 v[176:179], v147 offset:8448
	v_mfma_f32_16x16x32_bf16 v[126:129], v[156:159], v[184:187], v[126:129]
	v_mfma_f32_16x16x32_bf16 v[122:125], v[160:163], v[184:187], v[122:125]
	ds_read_b128 v[216:219], v145 offset:49152
	v_mfma_f32_16x16x32_bf16 v[118:121], v[156:159], v[192:195], v[118:121]
	v_mfma_f32_16x16x32_bf16 v[110:113], v[160:163], v[192:195], v[110:113]
	ds_read_b128 v[220:223], v145 offset:50176
	v_mfma_f32_16x16x32_bf16 v[102:105], v[156:159], v[200:203], v[102:105]
	v_mfma_f32_16x16x32_bf16 v[94:97], v[160:163], v[200:203], v[94:97]
	ds_read_b128 v[224:227], v145 offset:51200
	v_mfma_f32_16x16x32_bf16 v[86:89], v[156:159], v[208:211], v[86:89]
	v_mfma_f32_16x16x32_bf16 v[78:81], v[160:163], v[208:211], v[78:81]
	ds_read_b128 v[228:231], v145 offset:52224
	s_waitcnt lgkmcnt(4)
	v_mfma_f32_16x16x32_bf16 v[114:117], v[164:167], v[180:183], v[114:117]
	v_mfma_f32_16x16x32_bf16 v[106:109], v[168:171], v[180:183], v[106:109]
	ds_read_b128 v[232:235], v145 offset:53248
	v_mfma_f32_16x16x32_bf16 v[98:101], v[164:167], v[188:191], v[98:101]
	v_mfma_f32_16x16x32_bf16 v[90:93], v[168:171], v[188:191], v[90:93]
	ds_read_b128 v[236:239], v145 offset:54272
	v_mfma_f32_16x16x32_bf16 v[82:85], v[164:167], v[196:199], v[82:85]
	v_mfma_f32_16x16x32_bf16 v[74:77], v[168:171], v[196:199], v[74:77]
	ds_read_b128 v[240:243], v145 offset:55296
	v_mfma_f32_16x16x32_bf16 v[70:73], v[164:167], v[204:207], v[70:73]
	v_mfma_f32_16x16x32_bf16 v[66:69], v[168:171], v[204:207], v[66:69]
	ds_read_b128 v[244:247], v145 offset:56320
	v_mfma_f32_16x16x32_bf16 v[114:117], v[172:175], v[184:187], v[114:117]
	v_mfma_f32_16x16x32_bf16 v[106:109], v[176:179], v[184:187], v[106:109]
	v_mfma_f32_16x16x32_bf16 v[98:101], v[172:175], v[192:195], v[98:101]
	v_mfma_f32_16x16x32_bf16 v[90:93], v[176:179], v[192:195], v[90:93]
	v_mfma_f32_16x16x32_bf16 v[82:85], v[172:175], v[200:203], v[82:85]
	v_mfma_f32_16x16x32_bf16 v[74:77], v[176:179], v[200:203], v[74:77]
	v_mfma_f32_16x16x32_bf16 v[70:73], v[172:175], v[208:211], v[70:73]
	v_mfma_f32_16x16x32_bf16 v[66:69], v[176:179], v[208:211], v[66:69]
	s_waitcnt lgkmcnt(0)
	v_mfma_f32_16x16x32_bf16 v[62:65], v[148:151], v[216:219], v[62:65]
	v_mfma_f32_16x16x32_bf16 v[58:61], v[152:155], v[216:219], v[58:61]
	v_mfma_f32_16x16x32_bf16 v[54:57], v[148:151], v[224:227], v[54:57]
	v_mfma_f32_16x16x32_bf16 v[46:49], v[152:155], v[224:227], v[46:49]
	v_mfma_f32_16x16x32_bf16 v[38:41], v[148:151], v[232:235], v[38:41]
	v_mfma_f32_16x16x32_bf16 v[30:33], v[152:155], v[232:235], v[30:33]
	v_mfma_f32_16x16x32_bf16 v[22:25], v[148:151], v[240:243], v[22:25]
	v_mfma_f32_16x16x32_bf16 v[14:17], v[152:155], v[240:243], v[14:17]
	v_mfma_f32_16x16x32_bf16 v[62:65], v[156:159], v[220:223], v[62:65]
	v_mfma_f32_16x16x32_bf16 v[58:61], v[160:163], v[220:223], v[58:61]
	v_mfma_f32_16x16x32_bf16 v[54:57], v[156:159], v[228:231], v[54:57]
	v_mfma_f32_16x16x32_bf16 v[46:49], v[160:163], v[228:231], v[46:49]
	v_mfma_f32_16x16x32_bf16 v[38:41], v[156:159], v[236:239], v[38:41]
	v_mfma_f32_16x16x32_bf16 v[30:33], v[160:163], v[236:239], v[30:33]
	v_mfma_f32_16x16x32_bf16 v[22:25], v[156:159], v[244:247], v[22:25]
	v_mfma_f32_16x16x32_bf16 v[14:17], v[160:163], v[244:247], v[14:17]
	v_mfma_f32_16x16x32_bf16 v[50:53], v[164:167], v[216:219], v[50:53]
	v_mfma_f32_16x16x32_bf16 v[42:45], v[168:171], v[216:219], v[42:45]
	v_mfma_f32_16x16x32_bf16 v[34:37], v[164:167], v[224:227], v[34:37]
	v_mfma_f32_16x16x32_bf16 v[26:29], v[168:171], v[224:227], v[26:29]
	v_mfma_f32_16x16x32_bf16 v[18:21], v[164:167], v[232:235], v[18:21]
	v_mfma_f32_16x16x32_bf16 v[10:13], v[168:171], v[232:235], v[10:13]
	v_mfma_f32_16x16x32_bf16 v[6:9], v[164:167], v[240:243], v[6:9]
	v_mfma_f32_16x16x32_bf16 v[2:5], v[168:171], v[240:243], v[2:5]
	v_mfma_f32_16x16x32_bf16 v[50:53], v[172:175], v[220:223], v[50:53]
	v_mfma_f32_16x16x32_bf16 v[42:45], v[176:179], v[220:223], v[42:45]
	v_mfma_f32_16x16x32_bf16 v[34:37], v[172:175], v[228:231], v[34:37]
	v_mfma_f32_16x16x32_bf16 v[26:29], v[176:179], v[228:231], v[26:29]
	v_mfma_f32_16x16x32_bf16 v[18:21], v[172:175], v[236:239], v[18:21]
	v_mfma_f32_16x16x32_bf16 v[10:13], v[176:179], v[236:239], v[10:13]
	v_mfma_f32_16x16x32_bf16 v[6:9], v[172:175], v[244:247], v[6:9]
	v_mfma_f32_16x16x32_bf16 v[2:5], v[176:179], v[244:247], v[2:5]
	s_setprio 0
	s_waitcnt vmcnt(0)
	s_barrier
	s_add_i32 s2, s87, 2
	s_cmp_gt_u32 s87, 61
	s_cbranch_scc1 .LBB0_255
	s_mov_b32 s87, s2
	s_branch .LBB0_220
